# FFN1 K-loop: LDS-DMA loads use SGPR base + precomputed 32-bit VGPR offsets (no per-load 64-bit VALU address adds)
# baseline (speedup 1.0000x reference)
.LBB0_1910:
	v_readlane_b32 s10, v255, 26
	v_readlane_b32 s11, v255, 27
	s_mov_b32 s17, s11
	v_readlane_b32 s7, v255, 25
	s_mul_i32 s16, s7, 0x18000
	s_add_u32 s10, s28, 0xd000000
	s_mov_b32 s7, s17
	s_addc_u32 s11, s29, 0
	v_writelane_b32 v255, s6, 26
	s_lshl_b64 s[16:17], s[16:17], 2
	v_bfe_u32 v9, v7, 4, 2
	v_writelane_b32 v255, s7, 27
	s_add_u32 s7, s28, s16
	s_addc_u32 s17, s29, s17
	s_add_u32 s16, s7, 0x240000
	v_and_b32_e32 v8, 15, v7
	v_lshlrev_b32_e32 v10, 3, v9
	v_lshlrev_b32_e32 v9, 4, v9
	v_lshlrev_b32_e32 v7, 2, v7
	s_addc_u32 s17, s17, 0
	s_and_b32 s6, s6, 3
	v_lshl_or_b32 v139, s1, 6, v8
	v_lshl_or_b32 v8, v8, 6, v9
	s_lshl_b32 s1, s1, 13
	v_and_b32_e32 v7, 32, v7
	v_bitop3_b32 v11, v8, s1, v7 bitop3:0xde
	s_lshl_b32 s1, s6, 12
	v_bitop3_b32 v140, v8, s1, v7 bitop3:0xde
	v_lshl_add_u64 v[8:9], v[0:1], 0, s[90:91]
	s_add_i32 m0, s51, 0x18000
	s_waitcnt vmcnt(2)
	s_barrier
	global_load_lds_dwordx4 v[8:9], off
	v_lshl_add_u64 v[8:9], v[0:1], 0, s[92:93]
	s_add_i32 m0, s51, 0x1a000
	s_add_i32 s77, s51, 0x8000
	global_load_lds_dwordx4 v[8:9], off
	v_lshl_add_u64 v[8:9], v[2:3], 0, s[90:91]
	s_mov_b32 m0, s77
	s_add_i32 s78, s51, 0xa000
	global_load_lds_dwordx4 v[8:9], off
	v_lshl_add_u64 v[2:3], v[2:3], 0, s[92:93]
	s_mov_b32 m0, s78
	v_lshl_or_b32 v141, s6, 5, v10
	global_load_lds_dwordx4 v[2:3], off
	v_lshl_add_u64 v[2:3], v[0:1], 0, s[94:95]
	s_add_i32 m0, s51, 0x1c000
	v_lshl_add_u64 v[0:1], v[0:1], 0, s[96:97]
	global_load_lds_dwordx4 v[2:3], off
	s_add_i32 m0, s51, 0x1e000
	s_cmpk_lt_u32 s0, 0x100
	global_load_lds_dwordx4 v[0:1], off
	v_lshlrev_b32_e32 v0, 14, v5
	v_and_b32_e32 v0, 0xffff8000, v0
	s_waitcnt vmcnt(6)
	v_lshl_add_u32 v0, v4, 11, v0
	v_and_b32_e32 v1, 1, v5
	v_lshl_or_b32 v0, v1, 6, v0
	v_readlane_b32 s0, v254, 34
	s_cselect_b64 s[18:19], -1, 0
	v_lshl_add_u32 v130, v6, 1, v0
	v_mov_b32_e32 v131, v185
	s_mov_b32 s79, 0
	v_add_u32_e32 v142, 0, v11
	v_add_u32_e32 v234, s84, v130
	v_add_u32_e32 v235, s84, v184
	v_add_u32_e32 v236, s86, v184
	v_add_u32_e32 v237, s88, v184
	v_add_u32_e32 v238, s90, v184
	v_add_u32_e32 v239, s92, v184
	v_add_u32_e32 v240, s94, v184
	v_add_u32_e32 v241, s96, v184
	v_add_u32_e32 v242, s84, v128
	v_add_u32_e32 v243, s86, v128
	v_add_u32_e32 v244, s88, v128
	v_add_u32_e32 v245, s90, v128
	v_add_u32_e32 v246, s92, v128
	v_readlane_b32 s33, v254, 33
	s_mov_b32 s48, s0
	s_barrier
	v_readlane_b32 s1, v254, 35
	s_branch .LBB0_1913

.LBB0_1916:
	s_add_u32 s2, s54, 0xfffc0080
	s_addc_u32 s3, s55, -1
	s_add_i32 vcc_lo, 0, 0x10000
	s_cmp_eq_u32 s81, 12
	s_cselect_b32 s3, s0, s3
	s_cselect_b32 s2, s1, s2
	v_add_u32_e32 v136, vcc_lo, v140
	s_cselect_b32 s83, s23, s80
	s_cselect_b32 s82, s25, s49
	s_add_i32 vcc_hi, 0, 0x14000
	s_mov_b64 s[98:99], s[2:3]
	s_mov_b64 s[100:101], s[82:83]
	ds_read_b128 v[132:135], v136
	ds_read_b128 v[144:147], v136 offset:1024
	ds_read_b128 v[148:151], v136 offset:2048
	ds_read_b128 v[152:155], v136 offset:3072
	v_add_u32_e32 v136, vcc_hi, v140
	ds_read_b128 v[156:159], v136
	ds_read_b128 v[160:163], v136 offset:1024
	ds_read_b128 v[164:167], v136 offset:2048
	ds_read_b128 v[168:171], v136 offset:3072
	s_add_i32 m0, s51, 0xc000
	ds_read_b128 v[172:175], v142
	ds_read_b128 v[176:179], v142 offset:1024
	ds_read_b128 v[180:183], v142 offset:2048
	ds_read_b128 v[200:203], v142 offset:3072
	ds_read_b128 v[204:207], v142 offset:4096
	ds_read_b128 v[208:211], v142 offset:5120
	ds_read_b128 v[212:215], v142 offset:6144
	ds_read_b128 v[216:219], v142 offset:7168
	global_load_lds_dwordx4 v130, s[54:55]
	s_add_i32 m0, s51, 0xe000
	s_nop 0
	global_load_lds_dwordx4 v234, s[54:55]
	s_waitcnt vmcnt(8)
	s_waitcnt lgkmcnt(0)
	s_barrier
	s_waitcnt lgkmcnt(0)
	v_mfma_f32_16x16x32_bf16 v[124:127], v[132:135], v[172:175], v[124:127]
	v_mfma_f32_16x16x32_bf16 v[120:123], v[148:151], v[172:175], v[120:123]
	v_mfma_f32_16x16x32_bf16 v[108:111], v[132:135], v[180:183], v[108:111]
	v_mfma_f32_16x16x32_bf16 v[104:107], v[148:151], v[180:183], v[104:107]
	v_mfma_f32_16x16x32_bf16 v[92:95], v[132:135], v[204:207], v[92:95]
	v_mfma_f32_16x16x32_bf16 v[88:91], v[148:151], v[204:207], v[88:91]
	v_mfma_f32_16x16x32_bf16 v[76:79], v[132:135], v[212:215], v[76:79]
	v_mfma_f32_16x16x32_bf16 v[72:75], v[148:151], v[212:215], v[72:75]
	v_mfma_f32_16x16x32_bf16 v[124:127], v[144:147], v[176:179], v[124:127]
	v_mfma_f32_16x16x32_bf16 v[120:123], v[152:155], v[176:179], v[120:123]
	v_mfma_f32_16x16x32_bf16 v[108:111], v[144:147], v[200:203], v[108:111]
	v_mfma_f32_16x16x32_bf16 v[104:107], v[152:155], v[200:203], v[104:107]
	v_mfma_f32_16x16x32_bf16 v[92:95], v[144:147], v[208:211], v[92:95]
	v_mfma_f32_16x16x32_bf16 v[88:91], v[152:155], v[208:211], v[88:91]
	v_mfma_f32_16x16x32_bf16 v[76:79], v[144:147], v[216:219], v[76:79]
	v_mfma_f32_16x16x32_bf16 v[72:75], v[152:155], v[216:219], v[72:75]
	v_mfma_f32_16x16x32_bf16 v[116:119], v[156:159], v[172:175], v[116:119]
	v_mfma_f32_16x16x32_bf16 v[112:115], v[164:167], v[172:175], v[112:115]
	v_mfma_f32_16x16x32_bf16 v[100:103], v[156:159], v[180:183], v[100:103]
	v_mfma_f32_16x16x32_bf16 v[96:99], v[164:167], v[180:183], v[96:99]
	v_mfma_f32_16x16x32_bf16 v[84:87], v[156:159], v[204:207], v[84:87]
	v_mfma_f32_16x16x32_bf16 v[80:83], v[164:167], v[204:207], v[80:83]
	v_mfma_f32_16x16x32_bf16 v[68:71], v[156:159], v[212:215], v[68:71]
	v_mfma_f32_16x16x32_bf16 v[64:67], v[164:167], v[212:215], v[64:67]
	v_mfma_f32_16x16x32_bf16 v[116:119], v[160:163], v[176:179], v[116:119]
	v_mfma_f32_16x16x32_bf16 v[112:115], v[168:171], v[176:179], v[112:115]
	v_mfma_f32_16x16x32_bf16 v[100:103], v[160:163], v[200:203], v[100:103]
	v_mfma_f32_16x16x32_bf16 v[96:99], v[168:171], v[200:203], v[96:99]
	v_mfma_f32_16x16x32_bf16 v[84:87], v[160:163], v[208:211], v[84:87]
	v_mfma_f32_16x16x32_bf16 v[80:83], v[168:171], v[208:211], v[80:83]
	v_mfma_f32_16x16x32_bf16 v[68:71], v[160:163], v[216:219], v[68:71]
	v_mfma_f32_16x16x32_bf16 v[64:67], v[168:171], v[216:219], v[64:67]
	s_barrier
	s_add_i32 s82, vcc_lo, s50
	s_mov_b32 m0, s82
	ds_read_b128 v[172:175], v142 offset:16384
	ds_read_b128 v[176:179], v142 offset:17408
	ds_read_b128 v[180:183], v142 offset:18432
	ds_read_b128 v[200:203], v142 offset:19456
	ds_read_b128 v[204:207], v142 offset:20480
	ds_read_b128 v[208:211], v142 offset:21504
	ds_read_b128 v[212:215], v142 offset:22528
	ds_read_b128 v[216:219], v142 offset:23552
	global_load_lds_dwordx4 v184, s[100:101]
	s_add_i32 m0, s82, 0x2000
	s_add_i32 s82, vcc_hi, s50
	global_load_lds_dwordx4 v235, s[100:101]
	s_mov_b32 m0, s82
	s_nop 0
	global_load_lds_dwordx4 v236, s[100:101]
	s_add_i32 m0, s82, 0x2000
	s_nop 0
	global_load_lds_dwordx4 v237, s[100:101]
	s_mov_b32 m0, s51
	s_nop 0
	global_load_lds_dwordx4 v128, s[98:99]
	s_mov_b32 m0, s66
	s_nop 0
	global_load_lds_dwordx4 v242, s[98:99]
	s_waitcnt vmcnt(8)
	s_waitcnt lgkmcnt(0)
	s_barrier
	s_waitcnt lgkmcnt(0)
	v_mfma_f32_16x16x32_bf16 v[60:63], v[132:135], v[172:175], v[60:63]
	v_mfma_f32_16x16x32_bf16 v[56:59], v[148:151], v[172:175], v[56:59]
	v_mfma_f32_16x16x32_bf16 v[44:47], v[132:135], v[180:183], v[44:47]
	v_mfma_f32_16x16x32_bf16 v[40:43], v[148:151], v[180:183], v[40:43]
	v_mfma_f32_16x16x32_bf16 v[28:31], v[132:135], v[204:207], v[28:31]
	v_mfma_f32_16x16x32_bf16 v[24:27], v[148:151], v[204:207], v[24:27]
	v_mfma_f32_16x16x32_bf16 v[12:15], v[132:135], v[212:215], v[12:15]
	v_mfma_f32_16x16x32_bf16 v[8:11], v[148:151], v[212:215], v[8:11]
	v_mfma_f32_16x16x32_bf16 v[60:63], v[144:147], v[176:179], v[60:63]
	v_mfma_f32_16x16x32_bf16 v[56:59], v[152:155], v[176:179], v[56:59]
	v_mfma_f32_16x16x32_bf16 v[44:47], v[144:147], v[200:203], v[44:47]
	v_mfma_f32_16x16x32_bf16 v[40:43], v[152:155], v[200:203], v[40:43]
	v_mfma_f32_16x16x32_bf16 v[28:31], v[144:147], v[208:211], v[28:31]
	v_mfma_f32_16x16x32_bf16 v[24:27], v[152:155], v[208:211], v[24:27]
	v_mfma_f32_16x16x32_bf16 v[12:15], v[144:147], v[216:219], v[12:15]
	v_mfma_f32_16x16x32_bf16 v[8:11], v[152:155], v[216:219], v[8:11]
	v_mfma_f32_16x16x32_bf16 v[52:55], v[156:159], v[172:175], v[52:55]
	v_mfma_f32_16x16x32_bf16 v[48:51], v[164:167], v[172:175], v[48:51]
	v_mfma_f32_16x16x32_bf16 v[36:39], v[156:159], v[180:183], v[36:39]
	v_mfma_f32_16x16x32_bf16 v[32:35], v[164:167], v[180:183], v[32:35]
	v_mfma_f32_16x16x32_bf16 v[20:23], v[156:159], v[204:207], v[20:23]
	v_mfma_f32_16x16x32_bf16 v[16:19], v[164:167], v[204:207], v[16:19]
	v_mfma_f32_16x16x32_bf16 v[4:7], v[156:159], v[212:215], v[4:7]
	v_mfma_f32_16x16x32_bf16 v[0:3], v[164:167], v[212:215], v[0:3]
	v_mfma_f32_16x16x32_bf16 v[52:55], v[160:163], v[176:179], v[52:55]
	v_mfma_f32_16x16x32_bf16 v[48:51], v[168:171], v[176:179], v[48:51]
	v_mfma_f32_16x16x32_bf16 v[36:39], v[160:163], v[200:203], v[36:39]
	v_mfma_f32_16x16x32_bf16 v[32:35], v[168:171], v[200:203], v[32:35]
	v_mfma_f32_16x16x32_bf16 v[20:23], v[160:163], v[208:211], v[20:23]
	v_mfma_f32_16x16x32_bf16 v[16:19], v[168:171], v[208:211], v[16:19]
	v_mfma_f32_16x16x32_bf16 v[4:7], v[160:163], v[216:219], v[4:7]
	v_mfma_f32_16x16x32_bf16 v[0:3], v[168:171], v[216:219], v[0:3]
	s_barrier
	s_add_i32 s2, 0, 0x18000
	v_add_u32_e32 v143, s2, v140
	s_add_i32 s3, 0, 0x1c000
	ds_read_b128 v[132:135], v143
	ds_read_b128 v[144:147], v143 offset:1024
	ds_read_b128 v[148:151], v143 offset:2048
	ds_read_b128 v[152:155], v143 offset:3072
	v_add_u32_e32 v143, s3, v140
	ds_read_b128 v[156:159], v143
	ds_read_b128 v[160:163], v143 offset:1024
	ds_read_b128 v[164:167], v143 offset:2048
	ds_read_b128 v[168:171], v143 offset:3072
	s_mov_b32 m0, s67
	ds_read_b128 v[172:175], v142 offset:32768
	ds_read_b128 v[176:179], v142 offset:33792
	ds_read_b128 v[180:183], v142 offset:34816
	ds_read_b128 v[200:203], v142 offset:35840
	ds_read_b128 v[204:207], v142 offset:36864
	ds_read_b128 v[208:211], v142 offset:37888
	ds_read_b128 v[212:215], v142 offset:38912
	ds_read_b128 v[216:219], v142 offset:39936
	global_load_lds_dwordx4 v243, s[98:99]
	s_mov_b32 m0, s76
	s_nop 0
	global_load_lds_dwordx4 v244, s[98:99]
	s_waitcnt vmcnt(8)
	s_waitcnt lgkmcnt(0)
	s_barrier
	s_waitcnt lgkmcnt(0)
	v_mfma_f32_16x16x32_bf16 v[124:127], v[132:135], v[172:175], v[124:127]
	v_mfma_f32_16x16x32_bf16 v[120:123], v[148:151], v[172:175], v[120:123]
	v_mfma_f32_16x16x32_bf16 v[108:111], v[132:135], v[180:183], v[108:111]
	v_mfma_f32_16x16x32_bf16 v[104:107], v[148:151], v[180:183], v[104:107]
	v_mfma_f32_16x16x32_bf16 v[92:95], v[132:135], v[204:207], v[92:95]
	v_mfma_f32_16x16x32_bf16 v[88:91], v[148:151], v[204:207], v[88:91]
	v_mfma_f32_16x16x32_bf16 v[76:79], v[132:135], v[212:215], v[76:79]
	v_mfma_f32_16x16x32_bf16 v[72:75], v[148:151], v[212:215], v[72:75]
	v_mfma_f32_16x16x32_bf16 v[124:127], v[144:147], v[176:179], v[124:127]
	v_mfma_f32_16x16x32_bf16 v[120:123], v[152:155], v[176:179], v[120:123]
	v_mfma_f32_16x16x32_bf16 v[108:111], v[144:147], v[200:203], v[108:111]
	v_mfma_f32_16x16x32_bf16 v[104:107], v[152:155], v[200:203], v[104:107]
	v_mfma_f32_16x16x32_bf16 v[92:95], v[144:147], v[208:211], v[92:95]
	v_mfma_f32_16x16x32_bf16 v[88:91], v[152:155], v[208:211], v[88:91]
	v_mfma_f32_16x16x32_bf16 v[76:79], v[144:147], v[216:219], v[76:79]
	v_mfma_f32_16x16x32_bf16 v[72:75], v[152:155], v[216:219], v[72:75]
	v_mfma_f32_16x16x32_bf16 v[116:119], v[156:159], v[172:175], v[116:119]
	v_mfma_f32_16x16x32_bf16 v[112:115], v[164:167], v[172:175], v[112:115]
	v_mfma_f32_16x16x32_bf16 v[100:103], v[156:159], v[180:183], v[100:103]
	v_mfma_f32_16x16x32_bf16 v[96:99], v[164:167], v[180:183], v[96:99]
	v_mfma_f32_16x16x32_bf16 v[84:87], v[156:159], v[204:207], v[84:87]
	v_mfma_f32_16x16x32_bf16 v[80:83], v[164:167], v[204:207], v[80:83]
	v_mfma_f32_16x16x32_bf16 v[68:71], v[156:159], v[212:215], v[68:71]
	v_mfma_f32_16x16x32_bf16 v[64:67], v[164:167], v[212:215], v[64:67]
	v_mfma_f32_16x16x32_bf16 v[116:119], v[160:163], v[176:179], v[116:119]
	v_mfma_f32_16x16x32_bf16 v[112:115], v[168:171], v[176:179], v[112:115]
	v_mfma_f32_16x16x32_bf16 v[100:103], v[160:163], v[200:203], v[100:103]
	v_mfma_f32_16x16x32_bf16 v[96:99], v[168:171], v[200:203], v[96:99]
	v_mfma_f32_16x16x32_bf16 v[84:87], v[160:163], v[208:211], v[84:87]
	v_mfma_f32_16x16x32_bf16 v[80:83], v[168:171], v[208:211], v[80:83]
	v_mfma_f32_16x16x32_bf16 v[68:71], v[160:163], v[216:219], v[68:71]
	v_mfma_f32_16x16x32_bf16 v[64:67], v[168:171], v[216:219], v[64:67]
	s_barrier
	s_add_i32 s2, s2, s50
	s_mov_b32 m0, s2
	ds_read_b128 v[172:175], v142 offset:49152
	ds_read_b128 v[176:179], v142 offset:50176
	ds_read_b128 v[180:183], v142 offset:51200
	ds_read_b128 v[200:203], v142 offset:52224
	ds_read_b128 v[204:207], v142 offset:53248
	ds_read_b128 v[208:211], v142 offset:54272
	ds_read_b128 v[212:215], v142 offset:55296
	ds_read_b128 v[216:219], v142 offset:56320
	global_load_lds_dwordx4 v238, s[100:101]
	s_add_i32 m0, s2, 0x2000
	s_add_i32 s2, s3, s50
	global_load_lds_dwordx4 v239, s[100:101]
	s_mov_b32 m0, s2
	s_nop 0
	global_load_lds_dwordx4 v240, s[100:101]
	s_add_i32 m0, s2, 0x2000
	s_nop 0
	global_load_lds_dwordx4 v241, s[100:101]
	s_mov_b32 m0, s77
	s_nop 0
	global_load_lds_dwordx4 v245, s[98:99]
	s_mov_b32 m0, s78
	s_nop 0
	global_load_lds_dwordx4 v246, s[98:99]
	s_waitcnt vmcnt(8)
	s_waitcnt lgkmcnt(0)
	s_barrier
	s_waitcnt lgkmcnt(0)
	v_mfma_f32_16x16x32_bf16 v[60:63], v[132:135], v[172:175], v[60:63]
	v_mfma_f32_16x16x32_bf16 v[56:59], v[148:151], v[172:175], v[56:59]
	v_mfma_f32_16x16x32_bf16 v[44:47], v[132:135], v[180:183], v[44:47]
	v_mfma_f32_16x16x32_bf16 v[40:43], v[148:151], v[180:183], v[40:43]
	v_mfma_f32_16x16x32_bf16 v[28:31], v[132:135], v[204:207], v[28:31]
	v_mfma_f32_16x16x32_bf16 v[24:27], v[148:151], v[204:207], v[24:27]
	v_mfma_f32_16x16x32_bf16 v[12:15], v[132:135], v[212:215], v[12:15]
	v_mfma_f32_16x16x32_bf16 v[8:11], v[148:151], v[212:215], v[8:11]
	v_mfma_f32_16x16x32_bf16 v[60:63], v[144:147], v[176:179], v[60:63]
	v_mfma_f32_16x16x32_bf16 v[56:59], v[152:155], v[176:179], v[56:59]
	v_mfma_f32_16x16x32_bf16 v[44:47], v[144:147], v[200:203], v[44:47]
	v_mfma_f32_16x16x32_bf16 v[40:43], v[152:155], v[200:203], v[40:43]
	v_mfma_f32_16x16x32_bf16 v[28:31], v[144:147], v[208:211], v[28:31]
	v_mfma_f32_16x16x32_bf16 v[24:27], v[152:155], v[208:211], v[24:27]
	v_mfma_f32_16x16x32_bf16 v[12:15], v[144:147], v[216:219], v[12:15]
	v_mfma_f32_16x16x32_bf16 v[8:11], v[152:155], v[216:219], v[8:11]
	v_mfma_f32_16x16x32_bf16 v[52:55], v[156:159], v[172:175], v[52:55]
	v_mfma_f32_16x16x32_bf16 v[48:51], v[164:167], v[172:175], v[48:51]
	v_mfma_f32_16x16x32_bf16 v[36:39], v[156:159], v[180:183], v[36:39]
	v_mfma_f32_16x16x32_bf16 v[32:35], v[164:167], v[180:183], v[32:35]
	v_mfma_f32_16x16x32_bf16 v[20:23], v[156:159], v[204:207], v[20:23]
	v_mfma_f32_16x16x32_bf16 v[16:19], v[164:167], v[204:207], v[16:19]
	v_mfma_f32_16x16x32_bf16 v[4:7], v[156:159], v[212:215], v[4:7]
	v_mfma_f32_16x16x32_bf16 v[0:3], v[164:167], v[212:215], v[0:3]
	v_mfma_f32_16x16x32_bf16 v[52:55], v[160:163], v[176:179], v[52:55]
	v_mfma_f32_16x16x32_bf16 v[48:51], v[168:171], v[176:179], v[48:51]
	v_mfma_f32_16x16x32_bf16 v[36:39], v[160:163], v[200:203], v[36:39]
	v_mfma_f32_16x16x32_bf16 v[32:35], v[168:171], v[200:203], v[32:35]
	v_mfma_f32_16x16x32_bf16 v[20:23], v[160:163], v[208:211], v[20:23]
	v_mfma_f32_16x16x32_bf16 v[16:19], v[168:171], v[208:211], v[16:19]
	v_mfma_f32_16x16x32_bf16 v[4:7], v[160:163], v[216:219], v[4:7]
	v_mfma_f32_16x16x32_bf16 v[0:3], v[168:171], v[216:219], v[0:3]
	s_barrier
	s_add_i32 s81, s81, 2
	s_add_u32 s54, s54, 0x100
	s_addc_u32 s55, s55, 0
	s_add_u32 s49, s49, 0x100
	s_addc_u32 s80, s80, 0
	s_cmp_gt_u32 s81, 13
	s_cbranch_scc0 .LBB0_1916
	s_and_b64 vcc, exec, s[18:19]
	s_cbranch_vccz .LBB0_1919
	s_barrier

	.amdhsa_kernel _Z10hybrid_fwd4Args
		.amdhsa_group_segment_fixed_size 0
		.amdhsa_private_segment_fixed_size 0
		.amdhsa_kernarg_size 528
		.amdhsa_user_sgpr_count 2
		.amdhsa_user_sgpr_dispatch_ptr 0
		.amdhsa_user_sgpr_queue_ptr 0
		.amdhsa_user_sgpr_kernarg_segment_ptr 1
		.amdhsa_user_sgpr_dispatch_id 0
		.amdhsa_user_sgpr_kernarg_preload_length 0
		.amdhsa_user_sgpr_kernarg_preload_offset 0
		.amdhsa_user_sgpr_private_segment_size 0
		.amdhsa_uses_dynamic_stack 0
		.amdhsa_enable_private_segment 0
		.amdhsa_system_sgpr_workgroup_id_x 1
		.amdhsa_system_sgpr_workgroup_id_y 0
		.amdhsa_system_sgpr_workgroup_id_z 0
		.amdhsa_system_sgpr_workgroup_info 0
		.amdhsa_system_vgpr_workitem_id 2
		.amdhsa_next_free_vgpr 256
		.amdhsa_next_free_sgpr 102
		.amdhsa_accum_offset 256
		.amdhsa_reserve_vcc 1
		.amdhsa_float_round_mode_32 0
		.amdhsa_float_round_mode_16_64 0
		.amdhsa_float_denorm_mode_32 3
		.amdhsa_float_denorm_mode_16_64 3
		.amdhsa_dx10_clamp 1
		.amdhsa_ieee_mode 1
		.amdhsa_fp16_overflow 0
		.amdhsa_tg_split 0
		.amdhsa_exception_fp_ieee_invalid_op 0
		.amdhsa_exception_fp_denorm_src 0
		.amdhsa_exception_fp_ieee_div_zero 0
		.amdhsa_exception_fp_ieee_overflow 0
		.amdhsa_exception_fp_ieee_underflow 0
		.amdhsa_exception_fp_ieee_inexact 0
		.amdhsa_exception_int_div_zero 0
	.end_amdhsa_kernel

amdhsa.kernels:
  - .agpr_count:     0
    .args:
      - .offset:         0
        .size:           272
        .value_kind:     by_value
      - .offset:         272
        .size:           4
        .value_kind:     hidden_block_count_x
      - .offset:         276
        .size:           4
        .value_kind:     hidden_block_count_y
      - .offset:         280
        .size:           4
        .value_kind:     hidden_block_count_z
      - .offset:         284
        .size:           2
        .value_kind:     hidden_group_size_x
      - .offset:         286
        .size:           2
        .value_kind:     hidden_group_size_y
      - .offset:         288
        .size:           2
        .value_kind:     hidden_group_size_z
      - .offset:         290
        .size:           2
        .value_kind:     hidden_remainder_x
      - .offset:         292
        .size:           2
        .value_kind:     hidden_remainder_y
      - .offset:         294
        .size:           2
        .value_kind:     hidden_remainder_z
      - .offset:         312
        .size:           8
        .value_kind:     hidden_global_offset_x
      - .offset:         320
        .size:           8
        .value_kind:     hidden_global_offset_y
      - .offset:         328
        .size:           8
        .value_kind:     hidden_global_offset_z
      - .offset:         336
        .size:           2
        .value_kind:     hidden_grid_dims
      - .offset:         360
        .size:           8
        .value_kind:     hidden_multigrid_sync_arg
      - .offset:         392
        .size:           4
        .value_kind:     hidden_dynamic_lds_size
    .group_segment_fixed_size: 0
    .kernarg_segment_align: 8
    .kernarg_segment_size: 528
    .language:       OpenCL C
    .language_version:
      - 2
      - 0
    .max_flat_workgroup_size: 512
    .name:           _Z10hybrid_fwd4Args
    .private_segment_fixed_size: 0
    .sgpr_count:     108
    .sgpr_spill_count: 156
    .symbol:         _Z10hybrid_fwd4Args.kd
    .uniform_work_group_size: 1
    .uses_dynamic_stack: false
    .vgpr_count:     256
    .vgpr_spill_count: 0
    .wavefront_size: 64
